# grid barrier flat release: non-leader workgroups poll the cross-XCD generation word directly (one hop less); leader completes L2 writeback+invalidate before arriving cross-XCD
# baseline (speedup 1.0000x reference)
.Lgs0_b173:
	s_or_b64 exec, exec, s[18:19]
	v_cvt_f32_u32_e32 v4, v2
	s_waitcnt vmcnt(0)
	v_readfirstlane_b32 s18, v3
	v_sub_u32_e32 v3, 0, v2
	v_rcp_iflag_f32_e32 v4, v4
	v_add_u32_e32 v5, s18, v1
	v_mul_f32_e32 v4, 0x4f7ffffe, v4
	v_cvt_u32_f32_e32 v4, v4
	v_mul_lo_u32 v1, v3, v4
	v_mul_hi_u32 v1, v4, v1
	v_add_u32_e32 v1, v4, v1
	v_mul_hi_u32 v1, v5, v1
	v_mul_lo_u32 v3, v1, v2
	v_sub_u32_e32 v3, v5, v3
	v_add_u32_e32 v4, 1, v1
	v_cmp_ge_u32_e32 vcc, v3, v2
	s_nop 1
	v_cndmask_b32_e32 v1, v1, v4, vcc
	v_sub_u32_e32 v4, v3, v2
	v_cndmask_b32_e32 v3, v3, v4, vcc
	v_add_u32_e32 v4, 1, v1
	v_cmp_ge_u32_e32 vcc, v3, v2
	v_add_u32_e32 v3, 1, v5
	s_nop 0
	v_cndmask_b32_e32 v1, v1, v4, vcc
	v_mul_lo_u32 v4, v2, v1
	v_add_u32_e32 v2, v4, v2
	v_cmp_ne_u32_e32 vcc, v3, v2
	s_and_saveexec_b64 s[18:19], vcc
	s_xor_b64 s[18:19], exec, s[18:19]
	s_cbranch_execz .Lgs0_b187
	v_readlane_b32 s22, v255, 4
	v_readlane_b32 s23, v255, 5
	s_waitcnt lgkmcnt(0)
	s_nop 3
	global_load_dword v0, v17, s[22:23] sc1
	s_waitcnt vmcnt(0)
	v_cmp_eq_u32_e32 vcc, v0, v1
	s_and_saveexec_b64 s[22:23], vcc
	s_cbranch_execz .Lgs0_b186
	s_mov_b32 s24, 1
	s_mov_b64 s[28:29], 0
	s_branch .Lgs0_b177

.Lgs0_b179:
	v_readlane_b32 s26, v255, 4
	v_readlane_b32 s27, v255, 5
	s_add_i32 s24, s24, 1
	s_mov_b64 s[42:43], -1
	s_nop 2
	global_load_dword v0, v17, s[26:27] sc1
	s_waitcnt vmcnt(0)
	v_cmp_ne_u32_e32 vcc, v0, v1
	s_orn2_b64 s[40:41], vcc, exec
	s_branch .Lgs0_b176

.Lgs0_b187:
	s_andn2_saveexec_b64 s[18:19], s[18:19]
	s_cbranch_execz .Lgs0_end
	s_mov_b64 s[18:19], exec
	buffer_wbl2 sc1
	s_waitcnt lgkmcnt(0)
	s_waitcnt vmcnt(0)
	buffer_inv sc1
	s_waitcnt vmcnt(0)
	v_mbcnt_lo_u32_b32 v1, s18, 0
	v_mbcnt_hi_u32_b32 v1, s19, v1
	v_cmp_eq_u32_e32 vcc, 0, v1
	s_and_saveexec_b64 s[22:23], vcc
	s_cbranch_execz .Lgs0_b190
	s_bcnt1_i32_b64 s18, s[18:19]
	v_mov_b32_e32 v2, s18
	v_readlane_b32 s18, v255, 2
	v_readlane_b32 s19, v255, 3
	s_nop 4
	global_atomic_add v2, v17, v2, s[18:19] sc0

.LBB0_604:
	s_or_b64 exec, exec, s[18:19]
	v_cvt_f32_u32_e32 v4, v2
	s_waitcnt vmcnt(0)
	v_readfirstlane_b32 s18, v3
	v_sub_u32_e32 v3, 0, v2
	v_rcp_iflag_f32_e32 v4, v4
	v_add_u32_e32 v5, s18, v1
	v_mul_f32_e32 v4, 0x4f7ffffe, v4
	v_cvt_u32_f32_e32 v4, v4
	v_mul_lo_u32 v1, v3, v4
	v_mul_hi_u32 v1, v4, v1
	v_add_u32_e32 v1, v4, v1
	v_mul_hi_u32 v1, v5, v1
	v_mul_lo_u32 v3, v1, v2
	v_sub_u32_e32 v3, v5, v3
	v_add_u32_e32 v4, 1, v1
	v_cmp_ge_u32_e32 vcc, v3, v2
	s_nop 1
	v_cndmask_b32_e32 v1, v1, v4, vcc
	v_sub_u32_e32 v4, v3, v2
	v_cndmask_b32_e32 v3, v3, v4, vcc
	v_add_u32_e32 v4, 1, v1
	v_cmp_ge_u32_e32 vcc, v3, v2
	v_add_u32_e32 v3, 1, v5
	s_nop 0
	v_cndmask_b32_e32 v1, v1, v4, vcc
	v_mul_lo_u32 v4, v2, v1
	v_add_u32_e32 v2, v4, v2
	v_cmp_ne_u32_e32 vcc, v3, v2
	s_and_saveexec_b64 s[18:19], vcc
	s_xor_b64 s[18:19], exec, s[18:19]
	s_cbranch_execz .LBB0_618
	v_readlane_b32 s22, v255, 4
	v_readlane_b32 s23, v255, 5
	s_waitcnt lgkmcnt(0)
	s_nop 3
	global_load_dword v0, v17, s[22:23] sc1
	s_waitcnt vmcnt(0)
	v_cmp_eq_u32_e32 vcc, v0, v1
	s_and_saveexec_b64 s[22:23], vcc
	s_cbranch_execz .LBB0_617
	s_mov_b32 s24, 1
	s_mov_b64 s[26:27], 0
	s_branch .LBB0_608

.LBB0_610:
	v_readlane_b32 s36, v255, 4
	v_readlane_b32 s37, v255, 5
	s_add_i32 s24, s24, 1
	s_mov_b64 s[40:41], -1
	s_nop 2
	global_load_dword v0, v17, s[36:37] sc1
	s_waitcnt vmcnt(0)
	v_cmp_ne_u32_e32 vcc, v0, v1
	s_orn2_b64 s[38:39], vcc, exec
	s_branch .LBB0_607

.LBB0_674:
	s_or_b64 exec, exec, s[14:15]
	v_cvt_f32_u32_e32 v4, v2
	s_waitcnt vmcnt(0)
	v_readfirstlane_b32 s14, v3
	v_sub_u32_e32 v3, 0, v2
	v_rcp_iflag_f32_e32 v4, v4
	v_add_u32_e32 v5, s14, v1
	v_mul_f32_e32 v4, 0x4f7ffffe, v4
	v_cvt_u32_f32_e32 v4, v4
	v_mul_lo_u32 v1, v3, v4
	v_mul_hi_u32 v1, v4, v1
	v_add_u32_e32 v1, v4, v1
	v_mul_hi_u32 v1, v5, v1
	v_mul_lo_u32 v3, v1, v2
	v_sub_u32_e32 v3, v5, v3
	v_add_u32_e32 v4, 1, v1
	v_cmp_ge_u32_e32 vcc, v3, v2
	s_nop 1
	v_cndmask_b32_e32 v1, v1, v4, vcc
	v_sub_u32_e32 v4, v3, v2
	v_cndmask_b32_e32 v3, v3, v4, vcc
	v_add_u32_e32 v4, 1, v1
	v_cmp_ge_u32_e32 vcc, v3, v2
	v_add_u32_e32 v3, 1, v5
	s_nop 0
	v_cndmask_b32_e32 v1, v1, v4, vcc
	v_mul_lo_u32 v4, v2, v1
	v_add_u32_e32 v2, v4, v2
	v_cmp_ne_u32_e32 vcc, v3, v2
	s_and_saveexec_b64 s[14:15], vcc
	s_xor_b64 s[14:15], exec, s[14:15]
	s_cbranch_execz .LBB0_688
	v_readlane_b32 s18, v255, 4
	v_readlane_b32 s19, v255, 5
	s_waitcnt lgkmcnt(0)
	s_nop 3
	global_load_dword v0, v17, s[18:19] sc1
	s_waitcnt vmcnt(0)
	v_cmp_eq_u32_e32 vcc, v0, v1
	s_and_saveexec_b64 s[18:19], vcc
	s_cbranch_execz .LBB0_687
	s_mov_b32 s36, 1
	s_mov_b64 s[22:23], 0
	s_branch .LBB0_678

.LBB0_680:
	v_readlane_b32 s28, v255, 4
	v_readlane_b32 s29, v255, 5
	s_add_i32 s36, s36, 1
	s_mov_b64 s[38:39], -1
	s_nop 2
	global_load_dword v0, v17, s[28:29] sc1
	s_waitcnt vmcnt(0)
	v_cmp_ne_u32_e32 vcc, v0, v1
	s_orn2_b64 s[28:29], vcc, exec
	s_branch .LBB0_677

.LBB0_688:
	s_andn2_saveexec_b64 s[14:15], s[14:15]
	s_cbranch_execz .LBB0_708
	s_mov_b64 s[14:15], exec
	buffer_wbl2 sc1
	s_waitcnt lgkmcnt(0)
	s_waitcnt vmcnt(0)
	buffer_inv sc1
	s_waitcnt vmcnt(0)
	v_mbcnt_lo_u32_b32 v1, s14, 0
	v_mbcnt_hi_u32_b32 v1, s15, v1
	v_cmp_eq_u32_e32 vcc, 0, v1
	s_and_saveexec_b64 s[18:19], vcc
	s_cbranch_execz .LBB0_691
	s_bcnt1_i32_b64 s14, s[14:15]
	v_mov_b32_e32 v2, s14
	v_readlane_b32 s14, v255, 2
	v_readlane_b32 s15, v255, 3
	s_nop 4
	global_atomic_add v2, v17, v2, s[14:15] sc0

.LBB0_742:
	s_or_b64 exec, exec, s[14:15]
	v_cvt_f32_u32_e32 v4, v2
	s_waitcnt vmcnt(0)
	v_readfirstlane_b32 s14, v3
	v_sub_u32_e32 v3, 0, v2
	v_rcp_iflag_f32_e32 v4, v4
	v_add_u32_e32 v5, s14, v1
	v_mul_f32_e32 v4, 0x4f7ffffe, v4
	v_cvt_u32_f32_e32 v4, v4
	v_mul_lo_u32 v1, v3, v4
	v_mul_hi_u32 v1, v4, v1
	v_add_u32_e32 v1, v4, v1
	v_mul_hi_u32 v1, v5, v1
	v_mul_lo_u32 v3, v1, v2
	v_sub_u32_e32 v3, v5, v3
	v_add_u32_e32 v4, 1, v1
	v_cmp_ge_u32_e32 vcc, v3, v2
	s_nop 1
	v_cndmask_b32_e32 v1, v1, v4, vcc
	v_sub_u32_e32 v4, v3, v2
	v_cndmask_b32_e32 v3, v3, v4, vcc
	v_add_u32_e32 v4, 1, v1
	v_cmp_ge_u32_e32 vcc, v3, v2
	v_add_u32_e32 v3, 1, v5
	s_nop 0
	v_cndmask_b32_e32 v1, v1, v4, vcc
	v_mul_lo_u32 v4, v2, v1
	v_add_u32_e32 v2, v4, v2
	v_cmp_ne_u32_e32 vcc, v3, v2
	s_and_saveexec_b64 s[14:15], vcc
	s_xor_b64 s[14:15], exec, s[14:15]
	s_cbranch_execz .LBB0_756
	v_readlane_b32 s18, v255, 4
	v_readlane_b32 s19, v255, 5
	s_waitcnt lgkmcnt(0)
	s_nop 3
	global_load_dword v0, v17, s[18:19] sc1
	s_waitcnt vmcnt(0)
	v_cmp_eq_u32_e32 vcc, v0, v1
	s_and_saveexec_b64 s[18:19], vcc
	s_cbranch_execz .LBB0_755
	s_mov_b32 s24, 1
	s_mov_b64 s[22:23], 0
	s_branch .LBB0_746

.LBB0_748:
	v_readlane_b32 s28, v255, 4
	v_readlane_b32 s29, v255, 5
	s_add_i32 s24, s24, 1
	s_mov_b64 s[38:39], -1
	s_nop 2
	global_load_dword v0, v17, s[28:29] sc1
	s_waitcnt vmcnt(0)
	v_cmp_ne_u32_e32 vcc, v0, v1
	s_orn2_b64 s[28:29], vcc, exec
	s_branch .LBB0_745

.LBB0_1025:
	v_readlane_b32 s28, v255, 4
	v_readlane_b32 s29, v255, 5
	s_add_i32 s24, s24, 1
	s_mov_b64 s[36:37], -1
	s_nop 2
	global_load_dword v0, v17, s[28:29] sc1
	s_waitcnt vmcnt(0)
	v_cmp_ne_u32_e32 vcc, v0, v1
	s_orn2_b64 s[28:29], vcc, exec
	s_branch .LBB0_1022

.LBB0_1034:
	s_mov_b64 s[14:15], exec
	buffer_wbl2 sc1
	s_waitcnt lgkmcnt(0)
	s_waitcnt vmcnt(0)
	buffer_inv sc1
	s_waitcnt vmcnt(0)
	v_mbcnt_lo_u32_b32 v1, s14, 0
	v_mbcnt_hi_u32_b32 v1, s15, v1
	v_cmp_eq_u32_e32 vcc, 0, v1
	s_and_saveexec_b64 s[18:19], vcc
	s_cbranch_execz .LBB0_1036
	s_bcnt1_i32_b64 s14, s[14:15]
	v_mov_b32_e32 v2, s14
	v_readlane_b32 s14, v255, 2
	v_readlane_b32 s15, v255, 3
	s_nop 4
	global_atomic_add v2, v17, v2, s[14:15] sc0
